# MLA attention: the 64 packed O-rescale multiplies (v_pk_mul_f32 between MFMAs) split into scalar v_mul_f32 pairs, bit-identical
# speedup vs baseline: 1.0027x; 1.0027x over previous
; #define MFMA32(a, b, c) __builtin_amdgcn_mfma_f32_32x32x16_bf16((a), (b), (c), 0, 0, 0)
; template <int DQK, bool WIN>
; DI void attn_item(const u16* __restrict__ Qb, int ldq, const u16* __restrict__ Kb, int ldk, const u16* __restrict__ Vtb, int qb,
;                   float qscale, float sink2, const u16* __restrict__ zb, int ldz, u16* __restrict__ ob, int ldo, u16* lds) {
;     ...
;   auto tile_body = [&](int kt, int buf, auto mask_tag) {
;     constexpr bool MASK = decltype(mask_tag)::value;
;     const u16* ks = lds + buf * STG; const u16* vs = ks + KBUF;
;     const int k0 = kt * 64;
;     bool active = (k0 <= q0 + 31);
;     if (WIN) active = active && (k0 + 63 >= q0 - 127);
;     if (active) {
;       f32x16 st[2];
; #pragma unroll
;       for (int kb = 0; kb < 2; ++kb) {
; #pragma unroll
;         for (int i = 0; i < 16; ++i) st[kb][i] = 0.f;
; #pragma unroll
;         for (int s = 0; s < NKS; ++s) {
;           bf16x8 a = *(const bf16x8*)(ks + (kb * 32 + r) * KST + 16 * s + 8 * hh);
;           st[kb] = MFMA32(a, qf[s], st[kb]);
;         }
;       }
;     ...
;   for (int kt = kt_lo; kt <= kt_hi; kt += 2) {
;     if (kt + 2 <= kt_hi) gload(rkA, rvA, kt + 2);
;     if (WIN || kt >= 2 * qb) tile_body(kt, 0, std::true_type{}); else tile_body(kt, 0, std::false_type{});
.LBB0_233:
	s_add_i32 s0, s31, -1
	s_add_i32 s1, s20, 0xffffff40
	s_cmp_lt_u32 s0, s29
	v_cmp_le_i32_e64 s[8:9], s1, v154
	s_mov_b64 s[24:25], -1
	s_cbranch_scc1 .LBB0_239
	v_mov_b64_e32 v[64:65], v[16:17]
	v_mov_b64_e32 v[48:49], v[32:33]
	v_mov_b32_e32 v158, v157
	v_mov_b32_e32 v0, v142
	v_mov_b64_e32 v[62:63], v[14:15]
	v_mov_b64_e32 v[60:61], v[12:13]
	v_mov_b64_e32 v[58:59], v[10:11]
	v_mov_b64_e32 v[56:57], v[8:9]
	v_mov_b64_e32 v[54:55], v[6:7]
	v_mov_b64_e32 v[52:53], v[4:5]
	v_mov_b64_e32 v[50:51], v[2:3]
	v_mov_b64_e32 v[46:47], v[30:31]
	v_mov_b64_e32 v[44:45], v[28:29]
	v_mov_b64_e32 v[42:43], v[26:27]
	v_mov_b64_e32 v[40:41], v[24:25]
	v_mov_b64_e32 v[38:39], v[22:23]
	v_mov_b64_e32 v[36:37], v[20:21]
	v_mov_b64_e32 v[34:35], v[18:19]
	s_and_saveexec_b64 s[24:25], s[8:9]
	s_cbranch_execz .LBB0_238
	ds_read_b128 v[206:209], v155
	ds_read_b128 v[210:213], v155 offset:32
	ds_read_b128 v[214:217], v155 offset:64
	ds_read_b128 v[218:221], v155 offset:6688
	ds_read_b128 v[222:225], v155 offset:96
	ds_read_b128 v[226:229], v155 offset:128
	ds_read_b128 v[230:233], v155 offset:160
	ds_read_b128 v[234:237], v155 offset:6656
	ds_read_b128 v[238:241], v155 offset:6720
	ds_read_b128 v[242:245], v155 offset:6752
	ds_read_b128 v[246:249], v155 offset:6784
	ds_read_b128 v[250:253], v155 offset:6816
	v_mov_b32_e32 v196, v142
	s_waitcnt lgkmcnt(11)
	v_mfma_f32_32x32x16_bf16 v[50:65], v[206:209], v[66:69], 0
	s_waitcnt lgkmcnt(10)
	v_mfma_f32_32x32x16_bf16 v[50:65], v[210:213], v[70:73], v[50:65]
	s_waitcnt lgkmcnt(9)
	v_mfma_f32_32x32x16_bf16 v[50:65], v[214:217], v[74:77], v[50:65]
	s_waitcnt lgkmcnt(7)
	v_mfma_f32_32x32x16_bf16 v[50:65], v[222:225], v[78:81], v[50:65]
	s_waitcnt lgkmcnt(6)
	v_mfma_f32_32x32x16_bf16 v[50:65], v[226:229], v[82:85], v[50:65]
	s_waitcnt lgkmcnt(5)
	v_mfma_f32_32x32x16_bf16 v[50:65], v[230:233], v[86:89], v[50:65]
	s_waitcnt lgkmcnt(4)
	v_mfma_f32_32x32x16_bf16 v[34:49], v[234:237], v[66:69], 0
	v_mfma_f32_32x32x16_bf16 v[34:49], v[218:221], v[70:73], v[34:49]
	s_waitcnt lgkmcnt(3)
	v_mfma_f32_32x32x16_bf16 v[34:49], v[238:241], v[74:77], v[34:49]
	s_waitcnt lgkmcnt(2)
	v_mfma_f32_32x32x16_bf16 v[34:49], v[242:245], v[78:81], v[34:49]
	s_waitcnt lgkmcnt(1)
	v_mfma_f32_32x32x16_bf16 v[34:49], v[246:249], v[82:85], v[34:49]
	s_waitcnt lgkmcnt(0)
; template <int DQK, bool WIN>
; DI void attn_item(const u16* __restrict__ Qb, int ldq, const u16* __restrict__ Kb, int ldk, const u16* __restrict__ Vtb, int qb,
;                   float qscale, float sink2, const u16* __restrict__ zb, int ldz, u16* __restrict__ ob, int ldo, u16* lds) {
;     ...
;       float mx = -INFINITY;
; #pragma unroll
;       for (int kb = 0; kb < 2; ++kb)
; #pragma unroll
;         for (int i = 0; i < 16; ++i) {
;           float v = st[kb][i];
;           if (MASK) {
;             int kg = k0 + kb * 32 + (i & 3) + 8 * (i >> 2) + 4 * hh;
;             bool ok = kg <= qrow;
;             if (WIN) ok = ok && (qrow - kg < 128);
;             v = ok ? v : -INFINITY;
;             st[kb][i] = v;
;           }
;           mx = fmaxf(mx, v);
;         }
;       mx = fmaxf(mx, __shfl_xor(mx, 32));
;       const float mn = fmaxf(m, mx);
;       if (__any(mn != m)) {
;         const float alpha = __builtin_amdgcn_exp2f((m - mn) * qscale);
;         lsum *= alpha;
; #pragma unroll
;         for (int i = 0; i < 16; ++i) { o[0][i] *= alpha; o[1][i] *= alpha; }
;       }
	v_mfma_f32_32x32x16_bf16 v[34:49], v[250:253], v[86:89], v[34:49]
	v_add_u32_e32 v158, s20, v146
	v_add_u32_e32 v0, 0xffffff40, v158
	v_cmp_le_i32_e32 vcc, v0, v130
	s_nop 1
	v_cndmask_b32_e32 v159, v176, v50, vcc
	v_cmp_lt_i32_e32 vcc, v0, v130
	s_nop 1
	v_cndmask_b32_e32 v0, v176, v51, vcc
	v_add_u32_e32 v51, 0xffffff42, v158
	v_cmp_le_i32_e32 vcc, v51, v130
	v_add_u32_e32 v51, 0xffffff43, v158
	v_max3_f32 v50, v159, s94, v0
	v_cndmask_b32_e32 v161, v176, v52, vcc
	v_cmp_le_i32_e32 vcc, v51, v130
	v_add_u32_e32 v51, 0xffffff48, v158
	s_nop 0
	v_cndmask_b32_e32 v160, v176, v53, vcc
	v_cmp_le_i32_e32 vcc, v51, v130
	v_add_u32_e32 v51, 0xffffff49, v158
	v_max3_f32 v50, v50, v161, v160
	v_cndmask_b32_e32 v164, v176, v54, vcc
	v_cmp_le_i32_e32 vcc, v51, v130
	v_add_u32_e32 v51, 0xffffff4a, v158
	s_nop 0
	v_cndmask_b32_e32 v162, v176, v55, vcc
	v_cmp_le_i32_e32 vcc, v51, v130
	v_add_u32_e32 v51, 0xffffff4b, v158
	v_max3_f32 v50, v50, v164, v162
	v_cndmask_b32_e32 v165, v176, v56, vcc
	v_cmp_le_i32_e32 vcc, v51, v130
	v_add_u32_e32 v51, 0xffffff50, v158
	s_nop 0
	v_cndmask_b32_e32 v166, v176, v57, vcc
	v_cmp_le_i32_e32 vcc, v51, v130
	v_add_u32_e32 v51, 0xffffff51, v158
	v_max3_f32 v50, v50, v165, v166
	v_cndmask_b32_e32 v205, v176, v58, vcc
	v_cmp_le_i32_e32 vcc, v51, v130
	v_add_u32_e32 v51, 0xffffff52, v158
	s_nop 0
	v_cndmask_b32_e32 v203, v176, v59, vcc
	v_cmp_le_i32_e32 vcc, v51, v130
	v_add_u32_e32 v51, 0xffffff53, v158
	v_max3_f32 v50, v50, v205, v203
	v_cndmask_b32_e32 v204, v176, v60, vcc
	v_cmp_le_i32_e32 vcc, v51, v130
	v_add_u32_e32 v51, 0xffffff58, v158
	s_nop 0
	v_cndmask_b32_e32 v201, v176, v61, vcc
	v_cmp_le_i32_e32 vcc, v51, v130
	v_add_u32_e32 v51, 0xffffff59, v158
	v_max3_f32 v50, v50, v204, v201
	v_cndmask_b32_e32 v202, v176, v62, vcc
	v_cmp_le_i32_e32 vcc, v51, v130
	v_add_u32_e32 v51, 0xffffff5a, v158
	s_nop 0
	v_cndmask_b32_e32 v199, v176, v63, vcc
	v_cmp_le_i32_e32 vcc, v51, v130
	v_add_u32_e32 v51, 0xffffff5b, v158
	v_max3_f32 v50, v50, v202, v199
	v_cndmask_b32_e32 v200, v176, v64, vcc
	v_cmp_le_i32_e32 vcc, v51, v130
	v_add_u32_e32 v51, 0xffffff60, v158
	s_nop 0
	v_cndmask_b32_e32 v197, v176, v65, vcc
	v_cmp_le_i32_e32 vcc, v51, v130
	v_max3_f32 v50, v50, v200, v197
	s_nop 0
	v_cndmask_b32_e32 v198, v176, v34, vcc
	v_add_u32_e32 v34, 0xffffff61, v158
	v_cmp_le_i32_e32 vcc, v34, v130
	s_nop 1
	v_cndmask_b32_e32 v195, v176, v35, vcc
	v_add_u32_e32 v35, 0xffffff62, v158
	v_cmp_le_i32_e32 vcc, v35, v130
	v_add_u32_e32 v35, 0xffffff63, v158
	v_max3_f32 v34, v50, v198, v195
	v_cndmask_b32_e32 v194, v176, v36, vcc
	v_cmp_le_i32_e32 vcc, v35, v130
	v_add_u32_e32 v35, 0xffffff68, v158
	v_and_b32_e32 v36, 64, v172
	v_cndmask_b32_e32 v193, v176, v37, vcc
	v_cmp_le_i32_e32 vcc, v35, v130
	v_add_u32_e32 v35, 0xffffff69, v158
	v_max3_f32 v34, v34, v194, v193
	v_cndmask_b32_e32 v192, v176, v38, vcc
	v_cmp_le_i32_e32 vcc, v35, v130
	v_add_u32_e32 v35, 0xffffff6a, v158
	v_add_u32_e32 v36, 64, v36
	v_cndmask_b32_e32 v167, v176, v39, vcc
	v_cmp_le_i32_e32 vcc, v35, v130
	v_add_u32_e32 v35, 0xffffff6b, v158
	v_max3_f32 v34, v34, v192, v167
	v_cndmask_b32_e32 v182, v176, v40, vcc
	v_cmp_le_i32_e32 vcc, v35, v130
	v_add_u32_e32 v35, 0xffffff70, v158
	v_mov_b64_e32 v[64:65], v[16:17]
	v_cndmask_b32_e32 v183, v176, v41, vcc
	v_cmp_le_i32_e32 vcc, v35, v130
	v_add_u32_e32 v35, 0xffffff71, v158
	v_max3_f32 v34, v34, v182, v183
	v_cndmask_b32_e32 v184, v176, v42, vcc
	v_cmp_le_i32_e32 vcc, v35, v130
	v_add_u32_e32 v35, 0xffffff72, v158
	v_mov_b64_e32 v[62:63], v[14:15]
	v_cndmask_b32_e32 v185, v176, v43, vcc
	v_cmp_le_i32_e32 vcc, v35, v130
	v_add_u32_e32 v35, 0xffffff73, v158
	v_max3_f32 v34, v34, v184, v185
	v_cndmask_b32_e32 v186, v176, v44, vcc
	v_cmp_le_i32_e32 vcc, v35, v130
	v_add_u32_e32 v35, 0xffffff78, v158
	v_mov_b64_e32 v[60:61], v[12:13]
	v_cndmask_b32_e32 v187, v176, v45, vcc
	v_cmp_le_i32_e32 vcc, v35, v130
	v_add_u32_e32 v35, 0xffffff79, v158
	v_max3_f32 v34, v34, v186, v187
	v_cndmask_b32_e32 v188, v176, v46, vcc
	v_cmp_le_i32_e32 vcc, v35, v130
	v_add_u32_e32 v35, 0xffffff7a, v158
	v_mov_b64_e32 v[58:59], v[10:11]
	v_cndmask_b32_e32 v189, v176, v47, vcc
	v_cmp_le_i32_e32 vcc, v35, v130
	v_add_u32_e32 v35, 0xffffff7b, v158
	v_max3_f32 v34, v34, v188, v189
	v_cndmask_b32_e32 v190, v176, v48, vcc
	v_cmp_le_i32_e32 vcc, v35, v130
	v_xor_b32_e32 v35, 32, v172
	v_mov_b64_e32 v[56:57], v[8:9]
	v_cndmask_b32_e32 v191, v176, v49, vcc
	v_cmp_lt_i32_e32 vcc, v35, v36
	v_max3_f32 v34, v34, v190, v191
	v_mov_b64_e32 v[54:55], v[6:7]
	v_cndmask_b32_e32 v35, v172, v35, vcc
	v_lshlrev_b32_e32 v35, 2, v35
	v_mov_b32_e32 v35, v34
	s_nop 1
	v_permlane32_swap_b32 v35, v34
	v_mov_b64_e32 v[52:53], v[4:5]
	v_mov_b64_e32 v[50:51], v[2:3]
	s_waitcnt lgkmcnt(0)
	v_max3_f32 v158, v157, v34, v35
	v_mov_b64_e32 v[48:49], v[32:33]
	v_cmp_neq_f32_e32 vcc, v158, v157
	v_mov_b64_e32 v[46:47], v[30:31]
	v_mov_b64_e32 v[44:45], v[28:29]
	v_mov_b64_e32 v[42:43], v[26:27]
	v_mov_b64_e32 v[40:41], v[24:25]
	v_mov_b64_e32 v[38:39], v[22:23]
	v_mov_b64_e32 v[36:37], v[20:21]
	v_mov_b64_e32 v[34:35], v[18:19]
	s_cbranch_vccz .LBB0_237
	v_sub_f32_e32 v34, v157, v158
	v_mul_f32_e32 v34, 0x3e16c740, v34
	v_exp_f32_e32 v50, v34
	s_nop 0
	v_mul_f32_e32 v196, v142, v50
	v_mul_f32_e32 v48, v32, v50
	v_mul_f32_e32 v49, v33, v50
	v_mul_f32_e32 v46, v30, v50
	v_mul_f32_e32 v47, v31, v50
	v_mul_f32_e32 v44, v28, v50
	v_mul_f32_e32 v45, v29, v50
	v_mul_f32_e32 v42, v26, v50
	v_mul_f32_e32 v43, v27, v50
	v_mul_f32_e32 v40, v24, v50
	v_mul_f32_e32 v41, v25, v50
	v_mul_f32_e32 v38, v22, v50
	v_mul_f32_e32 v39, v23, v50
	v_mul_f32_e32 v36, v20, v50
	v_mul_f32_e32 v37, v21, v50
	v_mul_f32_e32 v34, v18, v50
	v_mul_f32_e32 v35, v19, v50
	v_mul_f32_e32 v64, v16, v50
	v_mul_f32_e32 v65, v17, v50
	v_mul_f32_e32 v62, v14, v50
	v_mul_f32_e32 v63, v15, v50
	v_mul_f32_e32 v60, v12, v50
	v_mul_f32_e32 v61, v13, v50
	v_mul_f32_e32 v58, v10, v50
	v_mul_f32_e32 v59, v11, v50
	v_mul_f32_e32 v56, v8, v50
	v_mul_f32_e32 v57, v9, v50
	v_mul_f32_e32 v54, v6, v50
	v_mul_f32_e32 v55, v7, v50
	v_mul_f32_e32 v52, v4, v50
	v_mul_f32_e32 v53, v5, v50
	v_mul_f32_e32 v51, v3, v50
	v_mul_f32_e32 v50, v2, v50

; #define MFMA32(a, b, c) __builtin_amdgcn_mfma_f32_32x32x16_bf16((a), (b), (c), 0, 0, 0)
; template <int DQK, bool WIN>
; DI void attn_item(const u16* __restrict__ Qb, int ldq, const u16* __restrict__ Kb, int ldk, const u16* __restrict__ Vtb, int qb,
;                   float qscale, float sink2, const u16* __restrict__ zb, int ldz, u16* __restrict__ ob, int ldo, u16* lds) {
;     ...
;   auto tile_body = [&](int kt, int buf, auto mask_tag) {
;     constexpr bool MASK = decltype(mask_tag)::value;
;     const u16* ks = lds + buf * STG; const u16* vs = ks + KBUF;
;     const int k0 = kt * 64;
;     bool active = (k0 <= q0 + 31);
;     if (WIN) active = active && (k0 + 63 >= q0 - 127);
;     if (active) {
;       f32x16 st[2];
; #pragma unroll
;       for (int kb = 0; kb < 2; ++kb) {
; #pragma unroll
;         for (int i = 0; i < 16; ++i) st[kb][i] = 0.f;
; #pragma unroll
;         for (int s = 0; s < NKS; ++s) {
;           bf16x8 a = *(const bf16x8*)(ks + (kb * 32 + r) * KST + 16 * s + 8 * hh);
;           st[kb] = MFMA32(a, qf[s], st[kb]);
;         }
;       }
;       float mx = -INFINITY;
; #pragma unroll
;       for (int kb = 0; kb < 2; ++kb)
; #pragma unroll
;         for (int i = 0; i < 16; ++i) {
;           float v = st[kb][i];
;           if (MASK) {
;             int kg = k0 + kb * 32 + (i & 3) + 8 * (i >> 2) + 4 * hh;
;             bool ok = kg <= qrow;
;             if (WIN) ok = ok && (qrow - kg < 128);
;             v = ok ? v : -INFINITY;
;             st[kb][i] = v;
;           }
;           mx = fmaxf(mx, v);
;         }
;       mx = fmaxf(mx, __shfl_xor(mx, 32));
;       const float mn = fmaxf(m, mx);
;       if (__any(mn != m)) {
;         const float alpha = __builtin_amdgcn_exp2f((m - mn) * qscale);
;         lsum *= alpha;
; #pragma unroll
;         for (int i = 0; i < 16; ++i) { o[0][i] *= alpha; o[1][i] *= alpha; }
;       }
.LBB0_239:
	s_andn2_b64 vcc, exec, s[24:25]
	s_cbranch_vccnz .LBB0_245
	s_and_saveexec_b64 s[24:25], s[8:9]
	s_cbranch_execz .LBB0_244
	ds_read_b128 v[164:167], v155
	ds_read_b128 v[182:185], v155 offset:32
	ds_read_b128 v[186:189], v155 offset:64
	ds_read_b128 v[190:193], v155 offset:6688
	ds_read_b128 v[194:197], v155 offset:96
	ds_read_b128 v[198:201], v155 offset:128
	ds_read_b128 v[202:205], v155 offset:160
	ds_read_b128 v[206:209], v155 offset:6656
	ds_read_b128 v[210:213], v155 offset:6720
	ds_read_b128 v[214:217], v155 offset:6752
	ds_read_b128 v[218:221], v155 offset:6784
	ds_read_b128 v[222:225], v155 offset:6816
	s_waitcnt lgkmcnt(11)
	v_mfma_f32_32x32x16_bf16 v[50:65], v[164:167], v[66:69], 0
	s_waitcnt lgkmcnt(10)
	v_mfma_f32_32x32x16_bf16 v[50:65], v[182:185], v[70:73], v[50:65]
	s_waitcnt lgkmcnt(9)
	v_mfma_f32_32x32x16_bf16 v[50:65], v[186:189], v[74:77], v[50:65]
	s_waitcnt lgkmcnt(7)
	v_mfma_f32_32x32x16_bf16 v[50:65], v[194:197], v[78:81], v[50:65]
	s_waitcnt lgkmcnt(6)
	v_mfma_f32_32x32x16_bf16 v[50:65], v[198:201], v[82:85], v[50:65]
	s_waitcnt lgkmcnt(5)
	v_mfma_f32_32x32x16_bf16 v[50:65], v[202:205], v[86:89], v[50:65]
	s_waitcnt lgkmcnt(4)
	v_mfma_f32_32x32x16_bf16 v[34:49], v[206:209], v[66:69], 0
	s_nop 8
	s_nop 0
	v_max3_f32 v0, v50, s94, v51
	v_max3_f32 v0, v0, v52, v53
	v_max3_f32 v0, v0, v54, v55
	v_max3_f32 v0, v0, v56, v57
	v_max3_f32 v0, v0, v58, v59
	v_max3_f32 v0, v0, v60, v61
	v_max3_f32 v0, v0, v62, v63
	v_mfma_f32_32x32x16_bf16 v[34:49], v[190:193], v[70:73], v[34:49]
	v_max3_f32 v0, v0, v64, v65
	s_waitcnt lgkmcnt(3)
	v_mfma_f32_32x32x16_bf16 v[34:49], v[210:213], v[74:77], v[34:49]
	s_waitcnt lgkmcnt(2)
	v_mfma_f32_32x32x16_bf16 v[34:49], v[214:217], v[78:81], v[34:49]
	s_waitcnt lgkmcnt(1)
	v_mfma_f32_32x32x16_bf16 v[34:49], v[218:221], v[82:85], v[34:49]
	s_waitcnt lgkmcnt(0)
	v_mfma_f32_32x32x16_bf16 v[34:49], v[222:225], v[86:89], v[34:49]
	v_and_b32_e32 v159, 64, v172
	v_xor_b32_e32 v158, 32, v172
	v_add_u32_e32 v159, 64, v159
	v_cmp_lt_i32_e32 vcc, v158, v159
	s_nop 7
	v_max3_f32 v0, v0, v34, v35
	v_max3_f32 v0, v0, v36, v37
	v_max3_f32 v0, v0, v38, v39
	v_max3_f32 v0, v0, v40, v41
	v_max3_f32 v0, v0, v42, v43
	v_max3_f32 v0, v0, v44, v45
	v_max3_f32 v0, v0, v46, v47
	v_cndmask_b32_e32 v158, v172, v158, vcc
	v_max3_f32 v0, v0, v48, v49
	v_lshlrev_b32_e32 v158, 2, v158
	v_mov_b32_e32 v158, v0
	s_nop 1
	v_permlane32_swap_b32 v158, v0
	s_waitcnt lgkmcnt(0)
	v_max3_f32 v0, v157, v0, v158
	v_cmp_neq_f32_e32 vcc, v0, v157
	s_cbranch_vccz .LBB0_243
	v_sub_f32_e32 v157, v157, v0
	v_mul_f32_e32 v157, 0x3e16c740, v157
	v_exp_f32_e32 v158, v157
	s_nop 0
	v_mul_f32_e32 v142, v142, v158
	v_mul_f32_e32 v32, v32, v158
	v_mul_f32_e32 v33, v33, v158
	v_mul_f32_e32 v30, v30, v158
	v_mul_f32_e32 v31, v31, v158
	v_mul_f32_e32 v28, v28, v158
	v_mul_f32_e32 v29, v29, v158
	v_mul_f32_e32 v26, v26, v158
	v_mul_f32_e32 v27, v27, v158
	v_mul_f32_e32 v24, v24, v158
	v_mul_f32_e32 v25, v25, v158
	v_mul_f32_e32 v22, v22, v158
	v_mul_f32_e32 v23, v23, v158
	v_mul_f32_e32 v20, v20, v158
	v_mul_f32_e32 v21, v21, v158
	v_mul_f32_e32 v18, v18, v158
	v_mul_f32_e32 v19, v19, v158
	v_mul_f32_e32 v16, v16, v158
	v_mul_f32_e32 v17, v17, v158
	v_mul_f32_e32 v14, v14, v158
	v_mul_f32_e32 v15, v15, v158
	v_mul_f32_e32 v12, v12, v158
	v_mul_f32_e32 v13, v13, v158
	v_mul_f32_e32 v10, v10, v158
	v_mul_f32_e32 v11, v11, v158
	v_mul_f32_e32 v8, v8, v158
	v_mul_f32_e32 v9, v9, v158
	v_mul_f32_e32 v6, v6, v158
	v_mul_f32_e32 v7, v7, v158
	v_mul_f32_e32 v4, v4, v158
	v_mul_f32_e32 v5, v5, v158
	v_mul_f32_e32 v2, v2, v158
	v_mul_f32_e32 v3, v3, v158

; #define MFMA32(a, b, c) __builtin_amdgcn_mfma_f32_32x32x16_bf16((a), (b), (c), 0, 0, 0)
; template <int DQK, bool WIN>
; DI void attn_item(const u16* __restrict__ Qb, int ldq, const u16* __restrict__ Kb, int ldk, const u16* __restrict__ Vtb, int qb,
;                   float qscale, float sink2, const u16* __restrict__ zb, int ldz, u16* __restrict__ ob, int ldo, u16* lds) {
;     ...
;   auto tile_body = [&](int kt, int buf, auto mask_tag) {
;     constexpr bool MASK = decltype(mask_tag)::value;
;     const u16* ks = lds + buf * STG; const u16* vs = ks + KBUF;
;     const int k0 = kt * 64;
;     bool active = (k0 <= q0 + 31);
;     if (WIN) active = active && (k0 + 63 >= q0 - 127);
;     if (active) {
;       f32x16 st[2];
; #pragma unroll
;       for (int kb = 0; kb < 2; ++kb) {
; #pragma unroll
;         for (int i = 0; i < 16; ++i) st[kb][i] = 0.f;
; #pragma unroll
;         for (int s = 0; s < NKS; ++s) {
;           bf16x8 a = *(const bf16x8*)(ks + (kb * 32 + r) * KST + 16 * s + 8 * hh);
;           st[kb] = MFMA32(a, qf[s], st[kb]);
;         }
;       }
;     ...
;     if (kt + 3 <= kt_hi) gload(rkB, rvB, kt + 3);
;     if (WIN || kt + 1 >= 2 * qb) tile_body(kt + 1, 1, std::true_type{}); else tile_body(kt + 1, 1, std::false_type{});
.LBB0_247:
	s_add_i32 s0, s20, 0xffffff80
	s_cmp_lt_u32 s31, s29
	v_cmp_le_i32_e64 s[8:9], s0, v154
	s_mov_b64 s[24:25], -1
	s_cbranch_scc1 .LBB0_257
	v_mov_b64_e32 v[50:51], v[2:3]
	v_mov_b64_e32 v[34:35], v[18:19]
	v_mov_b32_e32 v158, v157
	v_mov_b32_e32 v0, v142
	v_mov_b64_e32 v[52:53], v[4:5]
	v_mov_b64_e32 v[54:55], v[6:7]
	v_mov_b64_e32 v[56:57], v[8:9]
	v_mov_b64_e32 v[58:59], v[10:11]
	v_mov_b64_e32 v[60:61], v[12:13]
	v_mov_b64_e32 v[62:63], v[14:15]
	v_mov_b64_e32 v[64:65], v[16:17]
	v_mov_b64_e32 v[36:37], v[20:21]
	v_mov_b64_e32 v[38:39], v[22:23]
	v_mov_b64_e32 v[40:41], v[24:25]
	v_mov_b64_e32 v[42:43], v[26:27]
	v_mov_b64_e32 v[44:45], v[28:29]
	v_mov_b64_e32 v[46:47], v[30:31]
	v_mov_b64_e32 v[48:49], v[32:33]
	s_and_saveexec_b64 s[24:25], s[8:9]
	s_cbranch_execz .LBB0_252
	ds_read_b128 v[206:209], v155 offset:22528
	ds_read_b128 v[210:213], v155 offset:22560
	ds_read_b128 v[214:217], v155 offset:22592
	ds_read_b128 v[218:221], v155 offset:29216
	ds_read_b128 v[222:225], v155 offset:22624
	ds_read_b128 v[226:229], v155 offset:22656
	ds_read_b128 v[230:233], v155 offset:22688
	ds_read_b128 v[234:237], v155 offset:29184
	ds_read_b128 v[238:241], v155 offset:29248
	ds_read_b128 v[242:245], v155 offset:29280
	ds_read_b128 v[246:249], v155 offset:29312
	ds_read_b128 v[250:253], v155 offset:29344
	v_add_u32_e32 v142, s20, v146
	v_add_u32_e32 v157, 0xffffff80, v142
	v_cmp_le_i32_e32 vcc, v157, v130
	s_waitcnt lgkmcnt(11)
	v_mfma_f32_32x32x16_bf16 v[18:33], v[206:209], v[66:69], 0
	s_waitcnt lgkmcnt(10)
	v_mfma_f32_32x32x16_bf16 v[18:33], v[210:213], v[70:73], v[18:33]
	s_waitcnt lgkmcnt(9)
	v_mfma_f32_32x32x16_bf16 v[18:33], v[214:217], v[74:77], v[18:33]
	s_waitcnt lgkmcnt(7)
	v_mfma_f32_32x32x16_bf16 v[18:33], v[222:225], v[78:81], v[18:33]
	s_waitcnt lgkmcnt(6)
	v_mfma_f32_32x32x16_bf16 v[18:33], v[226:229], v[82:85], v[18:33]
	s_waitcnt lgkmcnt(5)
	v_mfma_f32_32x32x16_bf16 v[18:33], v[230:233], v[86:89], v[18:33]
	s_waitcnt lgkmcnt(4)
	v_mfma_f32_32x32x16_bf16 v[2:17], v[234:237], v[66:69], 0
	v_mfma_f32_32x32x16_bf16 v[2:17], v[218:221], v[70:73], v[2:17]
	s_waitcnt lgkmcnt(3)
	v_mfma_f32_32x32x16_bf16 v[2:17], v[238:241], v[74:77], v[2:17]
	s_waitcnt lgkmcnt(2)
	v_mfma_f32_32x32x16_bf16 v[2:17], v[242:245], v[78:81], v[2:17]
	s_waitcnt lgkmcnt(1)
	v_mfma_f32_32x32x16_bf16 v[2:17], v[246:249], v[82:85], v[2:17]
	s_waitcnt lgkmcnt(0)
; template <int DQK, bool WIN>
; DI void attn_item(const u16* __restrict__ Qb, int ldq, const u16* __restrict__ Kb, int ldk, const u16* __restrict__ Vtb, int qb,
;                   float qscale, float sink2, const u16* __restrict__ zb, int ldz, u16* __restrict__ ob, int ldo, u16* lds) {
;     ...
;       float mx = -INFINITY;
; #pragma unroll
;       for (int kb = 0; kb < 2; ++kb)
; #pragma unroll
;         for (int i = 0; i < 16; ++i) {
;           float v = st[kb][i];
;           if (MASK) {
;             int kg = k0 + kb * 32 + (i & 3) + 8 * (i >> 2) + 4 * hh;
;             bool ok = kg <= qrow;
;             if (WIN) ok = ok && (qrow - kg < 128);
;             v = ok ? v : -INFINITY;
;             st[kb][i] = v;
;           }
;           mx = fmaxf(mx, v);
;         }
;       mx = fmaxf(mx, __shfl_xor(mx, 32));
;       const float mn = fmaxf(m, mx);
;       if (__any(mn != m)) {
;         const float alpha = __builtin_amdgcn_exp2f((m - mn) * qscale);
;         lsum *= alpha;
; #pragma unroll
;         for (int i = 0; i < 16; ++i) { o[0][i] *= alpha; o[1][i] *= alpha; }
;       }
	v_mfma_f32_32x32x16_bf16 v[2:17], v[250:253], v[86:89], v[2:17]
	s_nop 0
	v_cndmask_b32_e32 v167, v176, v18, vcc
	v_cmp_lt_i32_e32 vcc, v157, v130
	s_nop 1
	v_cndmask_b32_e32 v166, v176, v19, vcc
	v_add_u32_e32 v19, 0xffffff82, v142
	v_cmp_le_i32_e32 vcc, v19, v130
	v_add_u32_e32 v19, 0xffffff83, v142
	v_max3_f32 v18, v167, s94, v166
	v_cndmask_b32_e32 v182, v176, v20, vcc
	v_cmp_le_i32_e32 vcc, v19, v130
	v_add_u32_e32 v19, 0xffffff88, v142
	s_nop 0
	v_cndmask_b32_e32 v183, v176, v21, vcc
	v_cmp_le_i32_e32 vcc, v19, v130
	v_add_u32_e32 v19, 0xffffff89, v142
	v_max3_f32 v18, v18, v182, v183
	v_cndmask_b32_e32 v185, v176, v22, vcc
	v_cmp_le_i32_e32 vcc, v19, v130
	v_add_u32_e32 v19, 0xffffff8a, v142
	s_nop 0
	v_cndmask_b32_e32 v186, v176, v23, vcc
	v_cmp_le_i32_e32 vcc, v19, v130
	v_add_u32_e32 v19, 0xffffff8b, v142
	v_max3_f32 v18, v18, v185, v186
	v_cndmask_b32_e32 v190, v176, v24, vcc
	v_cmp_le_i32_e32 vcc, v19, v130
	v_add_u32_e32 v19, 0xffffff90, v142
	s_nop 0
	v_cndmask_b32_e32 v191, v176, v25, vcc
	v_cmp_le_i32_e32 vcc, v19, v130
	v_add_u32_e32 v19, 0xffffff91, v142
	v_max3_f32 v18, v18, v190, v191
	v_cndmask_b32_e32 v201, v176, v26, vcc
	v_cmp_le_i32_e32 vcc, v19, v130
	v_add_u32_e32 v19, 0xffffff92, v142
	s_nop 0
	v_cndmask_b32_e32 v195, v176, v27, vcc
	v_cmp_le_i32_e32 vcc, v19, v130
	v_add_u32_e32 v19, 0xffffff93, v142
	v_max3_f32 v18, v18, v201, v195
	v_cndmask_b32_e32 v202, v176, v28, vcc
	v_cmp_le_i32_e32 vcc, v19, v130
	v_add_u32_e32 v19, 0xffffff98, v142
	s_nop 0
	v_cndmask_b32_e32 v196, v176, v29, vcc
	v_cmp_le_i32_e32 vcc, v19, v130
	v_add_u32_e32 v19, 0xffffff99, v142
	v_max3_f32 v18, v18, v202, v196
	v_cndmask_b32_e32 v203, v176, v30, vcc
	v_cmp_le_i32_e32 vcc, v19, v130
	v_add_u32_e32 v19, 0xffffff9a, v142
	s_nop 0
	v_cndmask_b32_e32 v197, v176, v31, vcc
	v_cmp_le_i32_e32 vcc, v19, v130
	v_add_u32_e32 v19, 0xffffff9b, v142
	v_max3_f32 v18, v18, v203, v197
	v_cndmask_b32_e32 v204, v176, v32, vcc
	v_cmp_le_i32_e32 vcc, v19, v130
	v_add_u32_e32 v19, 0xffffffa0, v142
	s_nop 0
	v_cndmask_b32_e32 v198, v176, v33, vcc
	v_cmp_le_i32_e32 vcc, v19, v130
	v_max3_f32 v18, v18, v204, v198
	s_nop 0
	v_cndmask_b32_e32 v205, v176, v2, vcc
	v_add_u32_e32 v2, 0xffffffa1, v142
	v_cmp_le_i32_e32 vcc, v2, v130
	s_nop 1
	v_cndmask_b32_e32 v199, v176, v3, vcc
	v_add_u32_e32 v3, 0xffffffa2, v142
	v_cmp_le_i32_e32 vcc, v3, v130
	v_add_u32_e32 v3, 0xffffffa3, v142
	v_max3_f32 v2, v18, v205, v199
	v_cndmask_b32_e32 v200, v176, v4, vcc
	v_cmp_le_i32_e32 vcc, v3, v130
	v_add_u32_e32 v3, 0xffffffa8, v142
	v_and_b32_e32 v4, 64, v172
	v_cndmask_b32_e32 v193, v176, v5, vcc
	v_cmp_le_i32_e32 vcc, v3, v130
	v_add_u32_e32 v3, 0xffffffa9, v142
	v_max3_f32 v2, v2, v200, v193
	v_cndmask_b32_e32 v194, v176, v6, vcc
	v_cmp_le_i32_e32 vcc, v3, v130
	v_add_u32_e32 v3, 0xffffffaa, v142
	v_add_u32_e32 v4, 64, v4
	v_cndmask_b32_e32 v192, v176, v7, vcc
	v_cmp_le_i32_e32 vcc, v3, v130
	v_add_u32_e32 v3, 0xffffffab, v142
	v_max3_f32 v2, v2, v194, v192
	v_cndmask_b32_e32 v187, v176, v8, vcc
	v_cmp_le_i32_e32 vcc, v3, v130
	v_add_u32_e32 v3, 0xffffffb0, v142
	v_mov_b64_e32 v[18:19], v[34:35]
	v_cndmask_b32_e32 v188, v176, v9, vcc
	v_cmp_le_i32_e32 vcc, v3, v130
	v_add_u32_e32 v3, 0xffffffb1, v142
	v_max3_f32 v2, v2, v187, v188
	v_cndmask_b32_e32 v189, v176, v10, vcc
	v_cmp_le_i32_e32 vcc, v3, v130
	v_add_u32_e32 v3, 0xffffffb2, v142
	v_mov_b64_e32 v[20:21], v[36:37]
	v_cndmask_b32_e32 v184, v176, v11, vcc
	v_cmp_le_i32_e32 vcc, v3, v130
	v_add_u32_e32 v3, 0xffffffb3, v142
	v_max3_f32 v2, v2, v189, v184
	v_cndmask_b32_e32 v165, v176, v12, vcc
	v_cmp_le_i32_e32 vcc, v3, v130
	v_add_u32_e32 v3, 0xffffffb8, v142
	v_mov_b64_e32 v[22:23], v[38:39]
	v_cndmask_b32_e32 v164, v176, v13, vcc
	v_cmp_le_i32_e32 vcc, v3, v130
	v_add_u32_e32 v3, 0xffffffb9, v142
	v_max3_f32 v2, v2, v165, v164
	v_cndmask_b32_e32 v160, v176, v14, vcc
	v_cmp_le_i32_e32 vcc, v3, v130
	v_add_u32_e32 v3, 0xffffffba, v142
	v_mov_b64_e32 v[24:25], v[40:41]
	v_cndmask_b32_e32 v161, v176, v15, vcc
	v_cmp_le_i32_e32 vcc, v3, v130
	v_add_u32_e32 v3, 0xffffffbb, v142
	v_max3_f32 v2, v2, v160, v161
	v_cndmask_b32_e32 v162, v176, v16, vcc
	v_cmp_le_i32_e32 vcc, v3, v130
	v_xor_b32_e32 v3, 32, v172
	v_mov_b64_e32 v[26:27], v[42:43]
	v_cndmask_b32_e32 v159, v176, v17, vcc
	v_cmp_lt_i32_e32 vcc, v3, v4
	v_max3_f32 v2, v2, v162, v159
	v_mov_b64_e32 v[28:29], v[44:45]
	v_cndmask_b32_e32 v3, v172, v3, vcc
	v_lshlrev_b32_e32 v3, 2, v3
	v_mov_b32_e32 v3, v2
	s_nop 1
	v_permlane32_swap_b32 v3, v2
	v_mov_b64_e32 v[30:31], v[46:47]
	v_mov_b64_e32 v[32:33], v[48:49]
	v_mov_b32_e32 v142, v0
	s_waitcnt lgkmcnt(0)
	v_max3_f32 v157, v158, v2, v3
	v_mov_b64_e32 v[2:3], v[50:51]
	v_cmp_neq_f32_e32 vcc, v157, v158
	v_mov_b64_e32 v[4:5], v[52:53]
	v_mov_b64_e32 v[6:7], v[54:55]
	v_mov_b64_e32 v[8:9], v[56:57]
	v_mov_b64_e32 v[10:11], v[58:59]
	v_mov_b64_e32 v[12:13], v[60:61]
	v_mov_b64_e32 v[14:15], v[62:63]
	v_mov_b64_e32 v[16:17], v[64:65]
	s_cbranch_vccz .LBB0_251
	v_sub_f32_e32 v2, v158, v157
	v_mul_f32_e32 v2, 0x3e16c740, v2
	v_exp_f32_e32 v2, v2
	s_nop 0
	v_mul_f32_e32 v142, v0, v2
	v_mul_f32_e32 v32, v48, v2
	v_mul_f32_e32 v33, v49, v2
	v_mul_f32_e32 v30, v46, v2
	v_mul_f32_e32 v31, v47, v2
	v_mul_f32_e32 v28, v44, v2
	v_mul_f32_e32 v29, v45, v2
	v_mul_f32_e32 v26, v42, v2
	v_mul_f32_e32 v27, v43, v2
	v_mul_f32_e32 v24, v40, v2
	v_mul_f32_e32 v25, v41, v2
	v_mul_f32_e32 v22, v38, v2
	v_mul_f32_e32 v23, v39, v2
	v_mul_f32_e32 v20, v36, v2
	v_mul_f32_e32 v21, v37, v2
	v_mul_f32_e32 v18, v34, v2
	v_mul_f32_e32 v19, v35, v2
	v_mul_f32_e32 v16, v64, v2
	v_mul_f32_e32 v17, v65, v2
	v_mul_f32_e32 v14, v62, v2
	v_mul_f32_e32 v15, v63, v2
	v_mul_f32_e32 v12, v60, v2
	v_mul_f32_e32 v13, v61, v2
	v_mul_f32_e32 v10, v58, v2
	v_mul_f32_e32 v11, v59, v2
	v_mul_f32_e32 v8, v56, v2
	v_mul_f32_e32 v9, v57, v2
	v_mul_f32_e32 v6, v54, v2
	v_mul_f32_e32 v7, v55, v2
	v_mul_f32_e32 v4, v52, v2
	v_mul_f32_e32 v5, v53, v2
	v_mul_f32_e32 v3, v51, v2
	v_mul_f32_e32 v2, v50, v2

; #define MFMA32(a, b, c) __builtin_amdgcn_mfma_f32_32x32x16_bf16((a), (b), (c), 0, 0, 0)
; template <int DQK, bool WIN>
; DI void attn_item(const u16* __restrict__ Qb, int ldq, const u16* __restrict__ Kb, int ldk, const u16* __restrict__ Vtb, int qb,
;                   float qscale, float sink2, const u16* __restrict__ zb, int ldz, u16* __restrict__ ob, int ldo, u16* lds) {
;     ...
;   auto tile_body = [&](int kt, int buf, auto mask_tag) {
;     constexpr bool MASK = decltype(mask_tag)::value;
;     const u16* ks = lds + buf * STG; const u16* vs = ks + KBUF;
;     const int k0 = kt * 64;
;     bool active = (k0 <= q0 + 31);
;     if (WIN) active = active && (k0 + 63 >= q0 - 127);
;     if (active) {
;       f32x16 st[2];
; #pragma unroll
;       for (int kb = 0; kb < 2; ++kb) {
; #pragma unroll
;         for (int i = 0; i < 16; ++i) st[kb][i] = 0.f;
; #pragma unroll
;         for (int s = 0; s < NKS; ++s) {
;           bf16x8 a = *(const bf16x8*)(ks + (kb * 32 + r) * KST + 16 * s + 8 * hh);
;           st[kb] = MFMA32(a, qf[s], st[kb]);
;         }
;       }
;       float mx = -INFINITY;
; #pragma unroll
;       for (int kb = 0; kb < 2; ++kb)
; #pragma unroll
;         for (int i = 0; i < 16; ++i) {
;           float v = st[kb][i];
;           if (MASK) {
;             int kg = k0 + kb * 32 + (i & 3) + 8 * (i >> 2) + 4 * hh;
;             bool ok = kg <= qrow;
;             if (WIN) ok = ok && (qrow - kg < 128);
;             v = ok ? v : -INFINITY;
;             st[kb][i] = v;
;           }
;           mx = fmaxf(mx, v);
;         }
;       mx = fmaxf(mx, __shfl_xor(mx, 32));
;       const float mn = fmaxf(m, mx);
;       if (__any(mn != m)) {
;         const float alpha = __builtin_amdgcn_exp2f((m - mn) * qscale);
;         lsum *= alpha;
; #pragma unroll
;         for (int i = 0; i < 16; ++i) { o[0][i] *= alpha; o[1][i] *= alpha; }
;       }
.LBB0_258:
	s_and_saveexec_b64 s[24:25], s[8:9]
	s_cbranch_execz .LBB0_262
	ds_read_b128 v[182:185], v155 offset:22528
	ds_read_b128 v[186:189], v155 offset:22560
	ds_read_b128 v[190:193], v155 offset:22592
	ds_read_b128 v[194:197], v155 offset:29216
	ds_read_b128 v[198:201], v155 offset:22624
	ds_read_b128 v[202:205], v155 offset:22656
	ds_read_b128 v[206:209], v155 offset:22688
	ds_read_b128 v[210:213], v155 offset:29184
	ds_read_b128 v[214:217], v155 offset:29248
	ds_read_b128 v[218:221], v155 offset:29280
	ds_read_b128 v[222:225], v155 offset:29312
	ds_read_b128 v[226:229], v155 offset:29344
	s_nop 7
	v_and_b32_e32 v159, 64, v172
	v_xor_b32_e32 v158, 32, v172
	v_add_u32_e32 v159, 64, v159
	s_waitcnt lgkmcnt(11)
	v_mfma_f32_32x32x16_bf16 v[34:49], v[182:185], v[66:69], 0
	v_cmp_lt_i32_e32 vcc, v158, v159
	s_nop 1
	v_cndmask_b32_e32 v158, v172, v158, vcc
	v_lshlrev_b32_e32 v158, 2, v158
	s_waitcnt lgkmcnt(10)
	v_mfma_f32_32x32x16_bf16 v[34:49], v[186:189], v[70:73], v[34:49]
	s_waitcnt lgkmcnt(9)
	v_mfma_f32_32x32x16_bf16 v[34:49], v[190:193], v[74:77], v[34:49]
	s_waitcnt lgkmcnt(7)
	v_mfma_f32_32x32x16_bf16 v[34:49], v[198:201], v[78:81], v[34:49]
	s_waitcnt lgkmcnt(6)
	v_mfma_f32_32x32x16_bf16 v[34:49], v[202:205], v[82:85], v[34:49]
	s_waitcnt lgkmcnt(5)
	v_mfma_f32_32x32x16_bf16 v[34:49], v[206:209], v[86:89], v[34:49]
	s_waitcnt lgkmcnt(4)
	v_mfma_f32_32x32x16_bf16 v[50:65], v[210:213], v[66:69], 0
	s_nop 8
	s_nop 0
	v_max3_f32 v0, v34, s94, v35
	v_max3_f32 v0, v0, v36, v37
	v_max3_f32 v0, v0, v38, v39
	v_max3_f32 v0, v0, v40, v41
	v_max3_f32 v0, v0, v42, v43
	v_max3_f32 v0, v0, v44, v45
	v_max3_f32 v0, v0, v46, v47
	v_mfma_f32_32x32x16_bf16 v[50:65], v[194:197], v[70:73], v[50:65]
	v_max3_f32 v0, v0, v48, v49
	s_waitcnt lgkmcnt(3)
	v_mfma_f32_32x32x16_bf16 v[50:65], v[214:217], v[74:77], v[50:65]
	s_waitcnt lgkmcnt(2)
	v_mfma_f32_32x32x16_bf16 v[50:65], v[218:221], v[78:81], v[50:65]
	s_waitcnt lgkmcnt(1)
	v_mfma_f32_32x32x16_bf16 v[50:65], v[222:225], v[82:85], v[50:65]
	s_waitcnt lgkmcnt(0)
	v_mfma_f32_32x32x16_bf16 v[50:65], v[226:229], v[86:89], v[50:65]
	s_nop 11
	v_max3_f32 v0, v0, v50, v51
	v_max3_f32 v0, v0, v52, v53
	v_max3_f32 v0, v0, v54, v55
	v_max3_f32 v0, v0, v56, v57
	v_max3_f32 v0, v0, v58, v59
	v_max3_f32 v0, v0, v60, v61
	v_max3_f32 v0, v0, v62, v63
	v_max3_f32 v0, v0, v64, v65
	v_mov_b32_e32 v158, v0
	s_nop 1
	v_permlane32_swap_b32 v158, v0
	s_waitcnt lgkmcnt(0)
	v_max3_f32 v0, v157, v0, v158
	v_cmp_neq_f32_e32 vcc, v0, v157
	s_cbranch_vccz .LBB0_261
	v_sub_f32_e32 v158, v157, v0
	v_mul_f32_e32 v158, 0x3e16c740, v158
	v_exp_f32_e32 v158, v158
	s_nop 0
	v_mul_f32_e32 v142, v142, v158
	v_mul_f32_e32 v32, v32, v158
	v_mul_f32_e32 v33, v33, v158
	v_mul_f32_e32 v30, v30, v158
	v_mul_f32_e32 v31, v31, v158
	v_mul_f32_e32 v28, v28, v158
	v_mul_f32_e32 v29, v29, v158
	v_mul_f32_e32 v26, v26, v158
	v_mul_f32_e32 v27, v27, v158
	v_mul_f32_e32 v24, v24, v158
	v_mul_f32_e32 v25, v25, v158
	v_mul_f32_e32 v22, v22, v158
	v_mul_f32_e32 v23, v23, v158
	v_mul_f32_e32 v20, v20, v158
	v_mul_f32_e32 v21, v21, v158
	v_mul_f32_e32 v18, v18, v158
	v_mul_f32_e32 v19, v19, v158
	v_mul_f32_e32 v16, v16, v158
	v_mul_f32_e32 v17, v17, v158
	v_mul_f32_e32 v14, v14, v158
	v_mul_f32_e32 v15, v15, v158
	v_mul_f32_e32 v12, v12, v158
	v_mul_f32_e32 v13, v13, v158
	v_mul_f32_e32 v10, v10, v158
	v_mul_f32_e32 v11, v11, v158
	v_mul_f32_e32 v8, v8, v158
	v_mul_f32_e32 v9, v9, v158
	v_mul_f32_e32 v6, v6, v158
	v_mul_f32_e32 v7, v7, v158
	v_mul_f32_e32 v4, v4, v158
	v_mul_f32_e32 v5, v5, v158
	v_mul_f32_e32 v2, v2, v158
	v_mul_f32_e32 v3, v3, v158
